# all changes combined: phase-0a cut-off at 5 items, 24 of 25 grid syncs on the two-level barrier
# speedup vs baseline: 1.0055x; 1.0021x over previous
; DI int bidx() { int b = blockIdx.x; asm volatile("" : "+s"(b)); return b; }
; DI void phase0a(const Params& p, char* lds) {
;     ...
;   for (int it = bidx(); it < NITEMS; it += gridDim.x) {
;     if (it < N_SSM) { ssm_tables(p, it >> 1, it & 1, lds); continue; }
.LBB0_3:
	v_readlane_b32 s0, v254, 5
	v_readlane_b32 vcc_lo, v255, 52
	v_readlane_b32 s8, v254, 4
	s_nop 3
	s_cmpk_lg_u32 s0, 0x100
	s_cbranch_scc1 .Lp0_orig
	s_cmp_lg_u32 vcc_lo, 0
	s_cbranch_scc1 .Lp0_extra_next
	s_add_i32 s74, s74, s0
	s_mul_i32 s9, s0, 24
	s_add_i32 s34, s34, s9
	s_cmp_lt_u32 s8, 64
	s_cbranch_scc0 .Lp0_big
	s_cmpk_lt_i32 s74, 0x500
	s_cbranch_scc1 .LBB0_4
	s_branch .LBB0_90

; DI int bidx() { int b = blockIdx.x; asm volatile("" : "+s"(b)); return b; }
; DI void phase0a(const Params& p, char* lds) {
;     ...
;   for (int it = bidx(); it < NITEMS; it += gridDim.x) {
;     if (it < N_SSM) { ssm_tables(p, it >> 1, it & 1, lds); continue; }
.Lp0_extra_set:
	s_cmpk_lt_i32 vcc_lo, 0x340
	s_cbranch_scc0 .LBB0_90
	s_add_i32 s9, vcc_lo, 1
	v_writelane_b32 v255, s9, 52
	s_and_b32 s9, vcc_lo, 63
	s_lshr_b32 vcc_lo, vcc_lo, 6
	s_add_i32 vcc_lo, vcc_lo, 5
	s_lshl_b32 vcc_lo, vcc_lo, 8
	s_add_i32 s74, vcc_lo, s9
	s_branch .LBB0_4
